# attention: first-chunk K/V staging loads hoisted to the top of the unit prologue
# baseline (speedup 1.0000x reference)
.LBB0_1167:
	s_bfe_u32 s70, s11, 0x20006
	s_lshl_b32 s71, s11, 7
	s_and_b32 s71, s71, 0x1f80
	s_lshl_b32 s72, s11, 5
	s_and_b32 s72, s72, 0xffffe000
	v_readlane_b32 s74, v243, 56
	v_readlane_b32 s75, v243, 57
	s_cmp_eq_u32 s71, 0
	s_cselect_b32 s73, 0, 0xffffff80
	s_or_b32 s72, s72, s71
	s_add_i32 s72, s72, s73
	s_lshl_b32 s70, s70, 7
	s_mov_b32 s71, 0
	s_movk_i32 s78, 0xc00
	v_add_u32_e32 v220, s72, v177
	v_mov_b64_e32 v[222:223], s[74:75]
	s_nop 0
	v_mad_i64_i32 v[220:221], s[76:77], v220, s78, v[222:223]
	v_lshl_add_u64 v[220:221], v[220:221], 0, s[70:71]
	v_lshl_add_u64 v[220:221], v[220:221], 0, v[144:145]
	global_load_dwordx4 v[204:207], v[220:221], off offset:2064
	global_load_dwordx4 v[208:211], v[220:221], off offset:2048
	global_load_dwordx4 v[212:215], v[220:221], off offset:2560
	global_load_dwordx4 v[216:219], v[220:221], off offset:2576
	s_bfe_u32 s1, s11, 0x20006
	s_lshl_b32 s0, s11, 7
	v_lshl_add_u32 v164, s1, 2, v175
	s_and_b32 s0, s0, 0x1f80
	s_lshl_b32 s2, s11, 5
	v_lshlrev_b32_e32 v162, 6, v164
	v_or_b32_e32 v18, s0, v176
	s_and_b32 s2, s2, 0xffffe000
	v_ashrrev_i32_e32 v163, 31, v162
	v_lshl_add_u64 v[64:65], v[162:163], 1, v[146:147]
	v_or3_b32 v160, s2, v149, v18
	s_movk_i32 s10, 0xc00
	v_mov_b32_e32 v16, v174
	v_lshrrev_b32_e32 v48, 6, v18
	v_mad_i64_i32 v[18:19], s[4:5], v160, s10, v[64:65]
	global_load_dwordx4 v[84:87], v[18:19], off
	global_load_dwordx4 v[88:91], v[18:19], off offset:32
	global_load_dwordx4 v[94:97], v[18:19], off offset:64
	global_load_dwordx4 v[98:101], v[18:19], off offset:96
	v_lshlrev_b32_e32 v60, 3, v16
	v_ashrrev_i32_e32 v61, 31, v60
	v_lshl_add_u64 v[16:17], v[60:61], 2, s[12:13]
	global_load_dwordx4 v[44:47], v[16:17], off
	global_load_dwordx4 v[40:43], v[16:17], off offset:16
	global_load_dwordx4 v[36:39], v[16:17], off offset:64
	global_load_dwordx4 v[32:35], v[16:17], off offset:80
	v_cvt_f32_i32_e32 v18, v60
	v_or_b32_e32 v51, 2, v60
	v_cvt_f32_i32_e32 v51, v51
	v_cvt_f32_ubyte0_e32 v61, v48
	v_mul_f32_e32 v18, 0xbf549a78, v18
	v_exp_f32_e32 v49, v18
	global_load_dwordx4 v[28:31], v[16:17], off offset:128
	global_load_dwordx4 v[24:27], v[16:17], off offset:144
	global_load_dwordx4 v[20:23], v[16:17], off offset:192
	s_nop 0
	global_load_dwordx4 v[16:19], v[16:17], off offset:208
	v_mul_f32_e32 v51, 0xbf549a78, v51
	v_exp_f32_e32 v53, v51
	v_mul_f32_e32 v165, 0.15915494, v49
	v_or_b32_e32 v49, 1, v60
	v_cvt_f32_i32_e32 v49, v49
	v_or_b32_e32 v57, 5, v60
	v_cvt_f32_i32_e32 v57, v57
	v_mul_f32_e32 v171, 0.15915494, v53
	v_mul_f32_e32 v49, 0xbf549a78, v49
	v_exp_f32_e32 v49, v49
	v_mul_f32_e32 v53, v171, v61
	v_mul_f32_e32 v57, 0xbf549a78, v57
	v_or_b32_e32 v59, 6, v60
	v_mul_f32_e32 v170, 0.15915494, v49
	v_mul_f32_e32 v52, v170, v61
	v_cos_f32_e32 v49, v52
	v_sin_f32_e32 v51, v52
	v_or_b32_e32 v52, 3, v60
	v_cvt_f32_i32_e32 v54, v52
	v_cos_f32_e32 v52, v53
	v_exp_f32_e32 v57, v57
	v_cvt_f32_i32_e32 v59, v59
	v_mul_f32_e32 v54, 0xbf549a78, v54
	v_exp_f32_e32 v55, v54
	v_sin_f32_e32 v54, v53
	v_or_b32_e32 v53, 4, v60
	v_cvt_f32_i32_e32 v56, v53
	v_mul_f32_e32 v187, 0.15915494, v57
	v_mul_f32_e32 v57, 0xbf549a78, v59
	v_exp_f32_e32 v63, v57
	v_mul_f32_e32 v56, 0xbf549a78, v56
	v_exp_f32_e32 v56, v56
	v_or_b32_e32 v57, 7, v60
	v_cvt_f32_i32_e32 v60, v57
	v_mul_f32_e32 v50, v165, v61
	v_mul_f32_e32 v172, 0.15915494, v55
	v_cos_f32_e32 v48, v50
	v_sin_f32_e32 v50, v50
	v_mul_f32_e32 v55, v172, v61
	v_mul_f32_e32 v173, 0.15915494, v56
	v_cos_f32_e32 v53, v55
	v_sin_f32_e32 v55, v55
	v_mul_f32_e32 v58, v173, v61
	v_mul_f32_e32 v62, v187, v61
	v_cos_f32_e32 v56, v58
	v_sin_f32_e32 v58, v58
	v_cos_f32_e32 v57, v62
	v_sin_f32_e32 v59, v62
	v_mul_f32_e32 v60, 0xbf549a78, v60
	v_mul_f32_e32 v92, 0.15915494, v63
	v_exp_f32_e32 v63, v60
	v_or_b32_e32 v166, 32, v160
	v_mad_i64_i32 v[64:65], s[4:5], v166, s10, v[64:65]
	v_mul_f32_e32 v93, 0.15915494, v63
	v_mul_f32_e32 v62, v92, v61
	v_mul_f32_e32 v63, v93, v61
	v_cos_f32_e32 v60, v62
	v_cos_f32_e32 v61, v63
	v_sin_f32_e32 v62, v62
	v_sin_f32_e32 v63, v63
	v_mul_f32_e32 v67, v165, v181
	v_mul_f32_e32 v68, v170, v181
	v_cos_f32_e32 v66, v67
	v_sin_f32_e32 v70, v67
	s_waitcnt vmcnt(11)
	v_lshlrev_b32_e32 v140, 16, v84
	v_and_b32_e32 v141, 0xffff0000, v84
	v_lshlrev_b32_e32 v132, 16, v85
	v_and_b32_e32 v133, 0xffff0000, v85
	v_pk_mul_f32 v[84:85], v[140:141], v[140:141]
	v_pk_mul_f32 v[134:135], v[132:133], v[132:133]
	v_add_f32_e32 v84, v84, v85
	v_lshlrev_b32_e32 v128, 16, v86
	v_and_b32_e32 v129, 0xffff0000, v86
	v_add_f32_e32 v84, v134, v84
	v_lshlrev_b32_e32 v120, 16, v87
	v_and_b32_e32 v121, 0xffff0000, v87
	v_pk_mul_f32 v[86:87], v[128:129], v[128:129]
	v_add_f32_e32 v84, v135, v84
	v_add_f32_e32 v84, v86, v84
	v_pk_mul_f32 v[122:123], v[120:121], v[120:121]
	v_add_f32_e32 v84, v87, v84
	s_waitcnt vmcnt(10)
	v_lshlrev_b32_e32 v142, 16, v88
	v_and_b32_e32 v143, 0xffff0000, v88
	v_add_f32_e32 v84, v122, v84
	v_lshlrev_b32_e32 v136, 16, v89
	v_and_b32_e32 v137, 0xffff0000, v89
	v_pk_mul_f32 v[88:89], v[142:143], v[142:143]
	v_add_f32_e32 v84, v123, v84
	v_add_f32_e32 v84, v88, v84
	v_pk_mul_f32 v[138:139], v[136:137], v[136:137]
	v_add_f32_e32 v84, v89, v84
	v_lshlrev_b32_e32 v130, 16, v90
	v_and_b32_e32 v131, 0xffff0000, v90
	v_add_f32_e32 v84, v138, v84
	v_lshlrev_b32_e32 v124, 16, v91
	v_and_b32_e32 v125, 0xffff0000, v91
	v_pk_mul_f32 v[90:91], v[130:131], v[130:131]
	v_add_f32_e32 v84, v139, v84
	v_add_f32_e32 v84, v90, v84
	v_pk_mul_f32 v[126:127], v[124:125], v[124:125]
	v_add_f32_e32 v84, v91, v84
	s_waitcnt vmcnt(9)
	v_lshlrev_b32_e32 v114, 16, v94
	v_and_b32_e32 v115, 0xffff0000, v94
	v_add_f32_e32 v84, v126, v84
	v_lshlrev_b32_e32 v108, 16, v95
	v_and_b32_e32 v109, 0xffff0000, v95
	v_pk_mul_f32 v[94:95], v[114:115], v[114:115]
	v_add_f32_e32 v84, v127, v84
	v_add_f32_e32 v84, v94, v84
	v_pk_mul_f32 v[110:111], v[108:109], v[108:109]
	v_add_f32_e32 v84, v95, v84
	v_lshlrev_b32_e32 v106, 16, v96
	v_and_b32_e32 v107, 0xffff0000, v96
	v_add_f32_e32 v84, v110, v84
	v_lshlrev_b32_e32 v80, 16, v97
	v_and_b32_e32 v81, 0xffff0000, v97
	v_pk_mul_f32 v[96:97], v[106:107], v[106:107]
	v_add_f32_e32 v84, v111, v84
	v_add_f32_e32 v84, v96, v84
	v_pk_mul_f32 v[102:103], v[80:81], v[80:81]
	v_add_f32_e32 v84, v97, v84
	s_waitcnt vmcnt(8)
	v_lshlrev_b32_e32 v118, 16, v98
	v_and_b32_e32 v119, 0xffff0000, v98
	v_add_f32_e32 v84, v102, v84
	v_lshlrev_b32_e32 v116, 16, v99
	v_and_b32_e32 v117, 0xffff0000, v99
	v_pk_mul_f32 v[98:99], v[118:119], v[118:119]
	v_add_f32_e32 v84, v103, v84
	v_add_f32_e32 v84, v98, v84
	v_pk_mul_f32 v[112:113], v[116:117], v[116:117]
	v_add_f32_e32 v84, v99, v84
	v_lshlrev_b32_e32 v82, 16, v100
	v_and_b32_e32 v83, 0xffff0000, v100
	v_add_f32_e32 v84, v112, v84
	v_lshlrev_b32_e32 v78, 16, v101
	v_and_b32_e32 v79, 0xffff0000, v101
	v_pk_mul_f32 v[100:101], v[82:83], v[82:83]
	v_add_f32_e32 v84, v113, v84
	v_add_f32_e32 v84, v100, v84
	v_pk_mul_f32 v[104:105], v[78:79], v[78:79]
	v_add_f32_e32 v84, v101, v84
	v_add_f32_e32 v84, v104, v84
	v_add_f32_e32 v85, v105, v84
	ds_bpermute_b32 v87, v202, v85
	v_cos_f32_e32 v67, v68
	v_sin_f32_e32 v71, v68
	v_mul_f32_e32 v69, v171, v181
	v_mul_f32_e32 v72, v172, v181
	s_waitcnt lgkmcnt(0)
	v_add_f32_e32 v85, v85, v87
	v_fmamk_f32 v85, v85, 0x3c800000, v186
	v_rsq_f32_e32 v88, v85
	v_cos_f32_e32 v68, v69
	v_sin_f32_e32 v74, v69
	v_cos_f32_e32 v69, v72
	v_mul_f32_e32 v94, 0x3e38aa3b, v88
	s_waitcnt vmcnt(7)
	v_pk_mul_f32 v[88:89], v[44:45], v[94:95] op_sel_hi:[1,0]
	s_waitcnt vmcnt(1)
	v_pk_mul_f32 v[122:123], v[20:21], v[94:95] op_sel_hi:[1,0]
	v_pk_mul_f32 v[96:97], v[88:89], v[140:141]
	v_pk_mul_f32 v[88:89], v[46:47], v[94:95] op_sel_hi:[1,0]
	v_pk_mul_f32 v[112:113], v[26:27], v[94:95] op_sel_hi:[1,0]
	v_pk_mul_f32 v[98:99], v[88:89], v[132:133]
	v_pk_mul_f32 v[88:89], v[40:41], v[94:95] op_sel_hi:[1,0]
	v_pk_mul_f32 v[80:81], v[112:113], v[80:81]
	v_pk_mul_f32 v[100:101], v[88:89], v[128:129]
	v_pk_mul_f32 v[88:89], v[42:43], v[94:95] op_sel_hi:[1,0]
	v_pk_mul_f32 v[128:129], v[122:123], v[118:119]
	v_pk_mul_f32 v[102:103], v[88:89], v[120:121]
	v_pk_mul_f32 v[88:89], v[36:37], v[94:95] op_sel_hi:[1,0]
	v_pk_mul_f32 v[118:119], v[22:23], v[94:95] op_sel_hi:[1,0]
	v_pk_mul_f32 v[104:105], v[88:89], v[142:143]
	v_pk_mul_f32 v[88:89], v[38:39], v[94:95] op_sel_hi:[1,0]
	v_sin_f32_e32 v75, v72
	v_pk_mul_f32 v[110:111], v[88:89], v[136:137]
	v_pk_mul_f32 v[88:89], v[32:33], v[94:95] op_sel_hi:[1,0]
	v_mul_f32_e32 v73, v173, v181
	v_pk_mul_f32 v[120:121], v[88:89], v[130:131]
	v_pk_mul_f32 v[88:89], v[34:35], v[94:95] op_sel_hi:[1,0]
	v_pk_mul_f32 v[130:131], v[118:119], v[116:117]
	v_pk_mul_f32 v[124:125], v[88:89], v[124:125]
	v_pk_mul_f32 v[88:89], v[28:29], v[94:95] op_sel_hi:[1,0]
	s_waitcnt vmcnt(0)
	v_pk_mul_f32 v[116:117], v[16:17], v[94:95] op_sel_hi:[1,0]
	v_pk_mul_f32 v[126:127], v[88:89], v[114:115]
	v_pk_mul_f32 v[88:89], v[30:31], v[94:95] op_sel_hi:[1,0]
	v_pk_mul_f32 v[82:83], v[116:117], v[82:83]
	v_pk_mul_f32 v[108:109], v[88:89], v[108:109]
	v_pk_mul_f32 v[88:89], v[24:25], v[94:95] op_sel_hi:[1,0]
	v_pk_mul_f32 v[94:95], v[18:19], v[94:95] op_sel_hi:[1,0]
	v_pk_mul_f32 v[116:117], v[58:59], v[120:121]
	v_pk_mul_f32 v[78:79], v[94:95], v[78:79]
	v_pk_mul_f32 v[94:95], v[48:49], v[104:105]
	v_pk_mul_f32 v[104:105], v[50:51], v[104:105]
	v_pk_fma_f32 v[94:95], v[50:51], v[96:97], v[94:95]
	v_pk_fma_f32 v[96:97], v[48:49], v[96:97], v[104:105] neg_lo:[0,0,1] neg_hi:[0,0,1]
	v_pk_mul_f32 v[104:105], v[52:53], v[110:111]
	v_pk_mul_f32 v[110:111], v[54:55], v[110:111]
	v_pk_fma_f32 v[104:105], v[54:55], v[98:99], v[104:105]
	v_pk_fma_f32 v[98:99], v[52:53], v[98:99], v[110:111] neg_lo:[0,0,1] neg_hi:[0,0,1]
	v_pk_mul_f32 v[110:111], v[56:57], v[120:121]
	v_pk_mul_f32 v[120:121], v[60:61], v[124:125]
	v_pk_fma_f32 v[110:111], v[58:59], v[100:101], v[110:111]
	v_pk_fma_f32 v[100:101], v[56:57], v[100:101], v[116:117] neg_lo:[0,0,1] neg_hi:[0,0,1]
	global_load_dwordx4 v[116:119], v[64:65], off
	v_pk_fma_f32 v[132:133], v[62:63], v[102:103], v[120:121]
	global_load_dwordx4 v[120:123], v[64:65], off offset:32
	v_pk_mul_f32 v[106:107], v[88:89], v[106:107]
	global_load_dwordx4 v[88:91], v[64:65], off offset:64
	global_load_dwordx4 v[112:115], v[64:65], off offset:96
	v_pk_mul_f32 v[64:65], v[62:63], v[124:125]
	v_mul_f32_e32 v77, v187, v181
	v_pk_fma_f32 v[64:65], v[60:61], v[102:103], v[64:65] neg_lo:[0,0,1] neg_hi:[0,0,1]
	v_pk_mul_f32 v[102:103], v[66:67], v[128:129]
	v_cos_f32_e32 v72, v73
	v_pk_fma_f32 v[124:125], v[70:71], v[126:127], v[102:103]
	v_pk_mul_f32 v[70:71], v[70:71], v[128:129]
	v_sin_f32_e32 v76, v73
	v_pk_fma_f32 v[66:67], v[66:67], v[126:127], v[70:71] neg_lo:[0,0,1] neg_hi:[0,0,1]
	v_pk_mul_f32 v[70:71], v[68:69], v[130:131]
	v_cos_f32_e32 v73, v77
	v_pk_fma_f32 v[70:71], v[74:75], v[108:109], v[70:71]
	v_pk_mul_f32 v[74:75], v[74:75], v[130:131]
	v_sin_f32_e32 v77, v77
	v_pk_fma_f32 v[68:69], v[68:69], v[108:109], v[74:75] neg_lo:[0,0,1] neg_hi:[0,0,1]
	v_cvt_pk_bf16_f32 v109, v70, v71
	v_mul_f32_e32 v70, v172, v182
	v_mul_f32_e32 v71, v173, v182
	v_mul_f32_e32 v86, v92, v181
	v_mul_f32_e32 v87, v93, v181
	v_cos_f32_e32 v84, v86
	v_sin_f32_e32 v86, v86
	v_cos_f32_e32 v85, v87
	v_sin_f32_e32 v87, v87
	v_pk_mul_f32 v[74:75], v[72:73], v[82:83]
	v_cvt_pk_bf16_f32 v96, v96, v97
	v_cvt_pk_bf16_f32 v97, v98, v99
	v_cvt_pk_bf16_f32 v98, v100, v101
	v_cvt_pk_bf16_f32 v101, v104, v105
	v_cvt_pk_bf16_f32 v104, v66, v67
	v_mul_f32_e32 v66, v170, v182
	v_mul_f32_e32 v67, v171, v182
	v_pk_fma_f32 v[74:75], v[76:77], v[106:107], v[74:75]
	v_pk_mul_f32 v[76:77], v[76:77], v[82:83]
	v_cvt_pk_bf16_f32 v103, v132, v133
	v_pk_fma_f32 v[72:73], v[72:73], v[106:107], v[76:77] neg_lo:[0,0,1] neg_hi:[0,0,1]
	v_pk_mul_f32 v[76:77], v[84:85], v[78:79]
	v_pk_mul_f32 v[78:79], v[86:87], v[78:79]
	v_pk_fma_f32 v[76:77], v[86:87], v[80:81], v[76:77]
	v_pk_fma_f32 v[78:79], v[84:85], v[80:81], v[78:79] neg_lo:[0,0,1] neg_hi:[0,0,1]
	v_cvt_pk_bf16_f32 v100, v94, v95
	v_cvt_pk_bf16_f32 v107, v78, v79
	v_cvt_pk_bf16_f32 v102, v110, v111
	v_cvt_pk_bf16_f32 v111, v76, v77
	v_cvt_pk_bf16_f32 v108, v124, v125
	s_cmp_eq_u32 s0, 0
	s_cselect_b64 s[4:5], -1, 0
	v_cvt_pk_bf16_f32 v99, v64, v65
	v_mul_f32_e32 v65, v165, v182
	v_cndmask_b32_e64 v165, 0, 1, s[4:5]
	s_and_b64 s[4:5], s[4:5], exec
	s_cselect_b32 s3, 0, 0xffffff80
	s_or_b32 s24, s2, s0
	s_add_i32 s4, s3, s24
	v_readlane_b32 s2, v243, 56
	v_readlane_b32 s3, v243, 57
	s_lshl_b32 s6, s1, 7
	s_barrier
	v_cvt_pk_bf16_f32 v105, v68, v69
	v_cos_f32_e32 v64, v65
	v_sin_f32_e32 v68, v65
	v_cos_f32_e32 v65, v66
	v_sin_f32_e32 v69, v66
	v_cvt_pk_bf16_f32 v106, v72, v73
	v_cvt_pk_bf16_f32 v110, v74, v75
	v_cos_f32_e32 v66, v67
	v_sin_f32_e32 v72, v67
	v_cos_f32_e32 v67, v70
	v_sin_f32_e32 v73, v70
	v_mul_f32_e32 v75, v187, v182
	v_cos_f32_e32 v70, v71
	v_sin_f32_e32 v74, v71
	s_waitcnt vmcnt(3)
	v_lshlrev_b32_e32 v194, 16, v116
	v_and_b32_e32 v195, 0xffff0000, v116
	v_lshlrev_b32_e32 v172, 16, v117
	v_and_b32_e32 v173, 0xffff0000, v117
	v_pk_mul_f32 v[116:117], v[194:195], v[194:195]
	v_pk_mul_f32 v[188:189], v[172:173], v[172:173]
	v_add_f32_e32 v116, v116, v117
	v_lshlrev_b32_e32 v142, 16, v118
	v_and_b32_e32 v143, 0xffff0000, v118
	v_add_f32_e32 v116, v188, v116
	v_lshlrev_b32_e32 v134, 16, v119
	v_and_b32_e32 v135, 0xffff0000, v119
	v_pk_mul_f32 v[118:119], v[142:143], v[142:143]
	v_add_f32_e32 v116, v189, v116
	v_add_f32_e32 v116, v118, v116
	v_pk_mul_f32 v[136:137], v[134:135], v[134:135]
	v_add_f32_e32 v116, v119, v116
	s_waitcnt vmcnt(2)
	v_lshlrev_b32_e32 v196, 16, v120
	v_and_b32_e32 v197, 0xffff0000, v120
	v_add_f32_e32 v116, v136, v116
	v_lshlrev_b32_e32 v190, 16, v121
	v_and_b32_e32 v191, 0xffff0000, v121
	v_pk_mul_f32 v[120:121], v[196:197], v[196:197]
	v_add_f32_e32 v116, v137, v116
	v_add_f32_e32 v116, v120, v116
	v_pk_mul_f32 v[192:193], v[190:191], v[190:191]
	v_add_f32_e32 v116, v121, v116
	v_lshlrev_b32_e32 v170, 16, v122
	v_and_b32_e32 v171, 0xffff0000, v122
	v_add_f32_e32 v116, v192, v116
	v_lshlrev_b32_e32 v138, 16, v123
	v_and_b32_e32 v139, 0xffff0000, v123
	v_pk_mul_f32 v[122:123], v[170:171], v[170:171]
	v_add_f32_e32 v116, v193, v116
	v_add_f32_e32 v116, v122, v116
	v_pk_mul_f32 v[140:141], v[138:139], v[138:139]
	v_add_f32_e32 v116, v123, v116
	s_waitcnt vmcnt(1)
	v_lshlrev_b32_e32 v78, 16, v91
	v_and_b32_e32 v79, 0xffff0000, v91
	v_lshlrev_b32_e32 v82, 16, v90
	v_and_b32_e32 v83, 0xffff0000, v90
	v_lshlrev_b32_e32 v90, 16, v88
	v_and_b32_e32 v91, 0xffff0000, v88
	v_add_f32_e32 v116, v140, v116
	v_pk_mul_f32 v[132:133], v[90:91], v[90:91]
	v_add_f32_e32 v116, v141, v116
	v_lshlrev_b32_e32 v86, 16, v89
	v_and_b32_e32 v87, 0xffff0000, v89
	v_add_f32_e32 v116, v132, v116
	v_pk_mul_f32 v[128:129], v[86:87], v[86:87]
	v_add_f32_e32 v116, v133, v116
	v_add_f32_e32 v116, v128, v116
	v_pk_mul_f32 v[126:127], v[82:83], v[82:83]
	v_add_f32_e32 v116, v129, v116
	v_add_f32_e32 v116, v126, v116
	v_pk_mul_f32 v[94:95], v[78:79], v[78:79]
	v_add_f32_e32 v116, v127, v116
	s_waitcnt vmcnt(0)
	v_lshlrev_b32_e32 v88, 16, v112
	v_and_b32_e32 v89, 0xffff0000, v112
	v_add_f32_e32 v94, v94, v116
	v_lshlrev_b32_e32 v84, 16, v113
	v_and_b32_e32 v85, 0xffff0000, v113
	v_pk_mul_f32 v[112:113], v[88:89], v[88:89]
	v_add_f32_e32 v94, v95, v94
	v_add_f32_e32 v94, v112, v94
	v_pk_mul_f32 v[130:131], v[84:85], v[84:85]
	v_add_f32_e32 v94, v113, v94
	v_lshlrev_b32_e32 v80, 16, v114
	v_and_b32_e32 v81, 0xffff0000, v114
	v_add_f32_e32 v94, v130, v94
	v_lshlrev_b32_e32 v76, 16, v115
	v_and_b32_e32 v77, 0xffff0000, v115
	v_pk_mul_f32 v[114:115], v[80:81], v[80:81]
	v_add_f32_e32 v94, v131, v94
	v_add_f32_e32 v94, v114, v94
	v_pk_mul_f32 v[124:125], v[76:77], v[76:77]
	v_add_f32_e32 v94, v115, v94
	v_add_f32_e32 v94, v124, v94
	v_add_f32_e32 v95, v125, v94
	ds_bpermute_b32 v112, v202, v95
	v_mov_b64_e32 v[120:121], s[2:3]
	v_or_b32_e32 v122, s4, v148
	v_cos_f32_e32 v71, v75
	v_sin_f32_e32 v75, v75
	s_waitcnt lgkmcnt(0)
	v_add_f32_e32 v95, v95, v112
	v_fmamk_f32 v95, v95, 0x3c800000, v186
	v_rsq_f32_e32 v112, v95
	v_mul_f32_e32 v94, v92, v182
	v_mul_f32_e32 v95, v93, v182
	v_cos_f32_e32 v92, v94
	v_mul_f32_e32 v128, 0x3e38aa3b, v112
	v_add_u32_e32 v112, s4, v177
	v_mad_i64_i32 v[112:113], s[2:3], v112, s10, v[120:121]
	v_mad_i64_i32 v[120:121], s[2:3], v122, s10, v[120:121]
	v_lshl_add_u64 v[112:113], v[112:113], 0, s[6:7]
	v_lshl_add_u64 v[120:121], v[120:121], 0, s[6:7]
	v_lshl_add_u64 v[116:117], v[112:113], 0, v[144:145]
	v_lshl_add_u64 v[124:125], v[112:113], 0, v[144:145]
	s_nop 0
	s_nop 0
	s_nop 0
	v_pk_mul_f32 v[36:37], v[36:37], v[128:129] op_sel_hi:[1,0]
	s_nop 0
	v_pk_mul_f32 v[44:45], v[44:45], v[128:129] op_sel_hi:[1,0]
	s_nop 0
	v_pk_mul_f32 v[36:37], v[36:37], v[196:197]
	v_pk_mul_f32 v[38:39], v[38:39], v[128:129] op_sel_hi:[1,0]
	v_pk_mul_f32 v[18:19], v[18:19], v[128:129] op_sel_hi:[1,0]
	v_pk_mul_f32 v[44:45], v[44:45], v[194:195]
	v_pk_mul_f32 v[46:47], v[46:47], v[128:129] op_sel_hi:[1,0]
	v_pk_mul_f32 v[38:39], v[38:39], v[190:191]
	v_pk_mul_f32 v[32:33], v[32:33], v[128:129] op_sel_hi:[1,0]
	v_pk_mul_f32 v[18:19], v[18:19], v[76:77]
	v_pk_mul_f32 v[76:77], v[48:49], v[36:37]
	v_pk_mul_f32 v[36:37], v[50:51], v[36:37]
	v_pk_mul_f32 v[46:47], v[46:47], v[172:173]
	v_pk_mul_f32 v[40:41], v[40:41], v[128:129] op_sel_hi:[1,0]
	v_pk_mul_f32 v[32:33], v[32:33], v[170:171]
	v_pk_mul_f32 v[34:35], v[34:35], v[128:129] op_sel_hi:[1,0]
	v_pk_fma_f32 v[76:77], v[50:51], v[44:45], v[76:77]
	v_pk_fma_f32 v[36:37], v[48:49], v[44:45], v[36:37] neg_lo:[0,0,1] neg_hi:[0,0,1]
	v_pk_mul_f32 v[44:45], v[52:53], v[38:39]
	v_pk_mul_f32 v[38:39], v[54:55], v[38:39]
	v_pk_mul_f32 v[40:41], v[40:41], v[142:143]
	v_pk_mul_f32 v[42:43], v[42:43], v[128:129] op_sel_hi:[1,0]
	v_pk_mul_f32 v[34:35], v[34:35], v[138:139]
	v_pk_mul_f32 v[20:21], v[20:21], v[128:129] op_sel_hi:[1,0]
	v_pk_fma_f32 v[44:45], v[54:55], v[46:47], v[44:45]
	v_pk_fma_f32 v[38:39], v[52:53], v[46:47], v[38:39] neg_lo:[0,0,1] neg_hi:[0,0,1]
	v_pk_mul_f32 v[46:47], v[56:57], v[32:33]
	v_pk_mul_f32 v[32:33], v[58:59], v[32:33]
	v_sin_f32_e32 v94, v94
	v_cos_f32_e32 v93, v95
	v_sin_f32_e32 v95, v95
	v_pk_mul_f32 v[42:43], v[42:43], v[134:135]
	v_pk_mul_f32 v[28:29], v[28:29], v[128:129] op_sel_hi:[1,0]
	v_pk_mul_f32 v[20:21], v[20:21], v[88:89]
	v_pk_mul_f32 v[22:23], v[22:23], v[128:129] op_sel_hi:[1,0]
	v_pk_fma_f32 v[46:47], v[58:59], v[40:41], v[46:47]
	v_pk_fma_f32 v[32:33], v[56:57], v[40:41], v[32:33] neg_lo:[0,0,1] neg_hi:[0,0,1]
	v_pk_mul_f32 v[40:41], v[60:61], v[34:35]
	v_pk_mul_f32 v[34:35], v[62:63], v[34:35]
	v_pk_mul_f32 v[28:29], v[28:29], v[90:91]
	v_pk_mul_f32 v[30:31], v[30:31], v[128:129] op_sel_hi:[1,0]
	v_pk_mul_f32 v[22:23], v[22:23], v[84:85]
	v_pk_mul_f32 v[16:17], v[16:17], v[128:129] op_sel_hi:[1,0]
	v_pk_fma_f32 v[40:41], v[62:63], v[42:43], v[40:41]
	v_pk_fma_f32 v[34:35], v[60:61], v[42:43], v[34:35] neg_lo:[0,0,1] neg_hi:[0,0,1]
	v_pk_mul_f32 v[42:43], v[64:65], v[20:21]
	v_pk_mul_f32 v[20:21], v[68:69], v[20:21]
	v_pk_mul_f32 v[30:31], v[30:31], v[86:87]
	v_pk_mul_f32 v[24:25], v[24:25], v[128:129] op_sel_hi:[1,0]
	v_pk_mul_f32 v[16:17], v[16:17], v[80:81]
	v_pk_fma_f32 v[42:43], v[68:69], v[28:29], v[42:43]
	v_pk_fma_f32 v[20:21], v[64:65], v[28:29], v[20:21] neg_lo:[0,0,1] neg_hi:[0,0,1]
	v_pk_mul_f32 v[28:29], v[66:67], v[22:23]
	v_pk_mul_f32 v[22:23], v[72:73], v[22:23]
	v_pk_mul_f32 v[24:25], v[24:25], v[82:83]
	v_pk_mul_f32 v[26:27], v[26:27], v[128:129] op_sel_hi:[1,0]
	v_pk_fma_f32 v[28:29], v[72:73], v[30:31], v[28:29]
	v_pk_fma_f32 v[22:23], v[66:67], v[30:31], v[22:23] neg_lo:[0,0,1] neg_hi:[0,0,1]
	v_pk_mul_f32 v[30:31], v[70:71], v[16:17]
	v_pk_mul_f32 v[16:17], v[74:75], v[16:17]
	v_pk_mul_f32 v[26:27], v[26:27], v[78:79]
	v_pk_fma_f32 v[30:31], v[74:75], v[24:25], v[30:31]
	v_pk_fma_f32 v[16:17], v[70:71], v[24:25], v[16:17] neg_lo:[0,0,1] neg_hi:[0,0,1]
	v_pk_mul_f32 v[24:25], v[92:93], v[18:19]
	v_pk_mul_f32 v[18:19], v[94:95], v[18:19]
	v_pk_fma_f32 v[24:25], v[94:95], v[26:27], v[24:25]
	v_pk_fma_f32 v[18:19], v[92:93], v[26:27], v[18:19] neg_lo:[0,0,1] neg_hi:[0,0,1]
	v_cvt_pk_bf16_f32 v142, v30, v31
	s_cmpk_eq_i32 s0, 0x1f80
	v_mov_b32_e32 v30, v145
	v_mov_b32_e32 v31, v145
	v_cvt_pk_bf16_f32 v128, v36, v37
	v_cvt_pk_bf16_f32 v129, v38, v39
	v_cvt_pk_bf16_f32 v130, v32, v33
	v_cvt_pk_bf16_f32 v131, v34, v35
	v_cvt_pk_bf16_f32 v132, v76, v77
	v_cvt_pk_bf16_f32 v133, v44, v45
	v_cvt_pk_bf16_f32 v134, v46, v47
	v_cvt_pk_bf16_f32 v135, v40, v41
	v_cvt_pk_bf16_f32 v136, v20, v21
	v_cvt_pk_bf16_f32 v137, v22, v23
	v_cvt_pk_bf16_f32 v138, v16, v17
	v_cvt_pk_bf16_f32 v139, v18, v19
	v_cvt_pk_bf16_f32 v140, v42, v43
	v_cvt_pk_bf16_f32 v141, v28, v29
	v_cvt_pk_bf16_f32 v143, v24, v25
	s_cselect_b32 s22, 3, 2
	v_writelane_b32 v243, s11, 60
	s_and_b32 s23, s11, 0xffffff00
	s_mov_b32 s1, s7
	v_mov_b32_e32 v16, v145
	v_mov_b32_e32 v17, v145
	v_mov_b32_e32 v18, v145
	v_mov_b32_e32 v19, v145
	v_mov_b32_e32 v20, v145
	v_mov_b32_e32 v21, v145
	v_mov_b32_e32 v22, v145
	v_mov_b32_e32 v23, v145
	v_mov_b32_e32 v24, v145
	v_mov_b32_e32 v25, v145
	v_mov_b32_e32 v26, v145
	v_mov_b32_e32 v27, v145
	v_mov_b32_e32 v28, v145
	v_mov_b32_e32 v29, v145
	v_mov_b64_e32 v[46:47], v[30:31]
	v_mov_b64_e32 v[62:63], v[30:31]
	v_mov_b64_e32 v[78:79], v[30:31]
	v_ashrrev_i32_e32 v161, 31, v160
	v_ashrrev_i32_e32 v167, 31, v166
	s_mov_b32 s33, 0
	v_readfirstlane_b32 s25, v165
	s_add_i32 s23, s23, 0xfe80
	s_addk_i32 s24, 0xff80
	v_lshl_add_u64 v[170:171], v[156:157], 0, s[6:7]
	v_writelane_b32 v243, s0, 50
	v_lshl_add_u64 v[172:173], v[158:159], 0, s[6:7]
	v_mov_b64_e32 v[44:45], v[28:29]
	v_mov_b64_e32 v[42:43], v[26:27]
	v_mov_b64_e32 v[40:41], v[24:25]
	v_mov_b64_e32 v[38:39], v[22:23]
	v_mov_b64_e32 v[36:37], v[20:21]
	v_mov_b64_e32 v[34:35], v[18:19]
	v_mov_b64_e32 v[32:33], v[16:17]
	v_mov_b64_e32 v[60:61], v[28:29]
	v_mov_b64_e32 v[58:59], v[26:27]
	v_mov_b64_e32 v[56:57], v[24:25]
	v_mov_b64_e32 v[54:55], v[22:23]
	v_mov_b64_e32 v[52:53], v[20:21]
	v_mov_b64_e32 v[50:51], v[18:19]
	v_mov_b64_e32 v[48:49], v[16:17]
	v_mov_b64_e32 v[76:77], v[28:29]
	v_mov_b64_e32 v[74:75], v[26:27]
	v_mov_b64_e32 v[72:73], v[24:25]
	v_mov_b64_e32 v[70:71], v[22:23]
	v_mov_b64_e32 v[68:69], v[20:21]
	v_mov_b64_e32 v[66:67], v[18:19]
	v_mov_b64_e32 v[64:65], v[16:17]
	v_mov_b32_e32 v187, 0
	v_mov_b32_e32 v188, 0
	s_waitcnt vmcnt(2)
	ds_write_b128 v179, v[208:211]
	ds_write_b128 v179, v[204:207] offset:16
	s_waitcnt vmcnt(1)
	ds_write_b16 v153, v212 offset:18432
	ds_write_b16_d16_hi v153, v212 offset:18696
	ds_write_b16 v153, v213 offset:18960
	ds_write_b16_d16_hi v153, v213 offset:19224
	ds_write_b16 v153, v214 offset:19488
	ds_write_b16_d16_hi v153, v214 offset:19752
	ds_write_b16 v153, v215 offset:20016
	ds_write_b16_d16_hi v153, v215 offset:20280
	s_waitcnt vmcnt(0)
	ds_write_b16 v153, v216 offset:20544
	ds_write_b16_d16_hi v153, v216 offset:20808
	ds_write_b16 v153, v217 offset:21072
	ds_write_b16_d16_hi v153, v217 offset:21336
	ds_write_b16 v153, v218 offset:21600
	ds_write_b16_d16_hi v153, v218 offset:21864
	ds_write_b16 v153, v219 offset:22128
	ds_write_b16_d16_hi v153, v219 offset:22392
	s_waitcnt lgkmcnt(0)
	s_barrier
	v_writelane_b32 v243, s1, 51

.Lat_m1_nodiag:
	v_add_f32_e32 v189, v80, v81
	v_add_f32_e32 v190, v82, v83
	v_add_f32_e32 v191, v84, v85
	v_add_f32_e32 v192, v86, v87
	v_add_f32_e32 v193, v88, v89
	v_add_f32_e32 v194, v90, v91
	v_add_f32_e32 v195, v92, v93
	v_add_f32_e32 v196, v94, v95
	v_cvt_pk_bf16_f32 v80, v80, v81
	v_cvt_pk_bf16_f32 v81, v82, v83
	v_cvt_pk_bf16_f32 v82, v84, v85
	v_cvt_pk_bf16_f32 v83, v86, v87
	v_cvt_pk_bf16_f32 v84, v88, v89
	v_cvt_pk_bf16_f32 v85, v90, v91
	v_cvt_pk_bf16_f32 v86, v92, v93
	v_cvt_pk_bf16_f32 v87, v94, v95
	v_add_f32_e32 v189, v189, v190
	v_add_f32_e32 v191, v191, v192
	v_add_f32_e32 v193, v193, v194
	v_add_f32_e32 v195, v195, v196
	v_add_f32_e32 v189, v189, v191
	v_add_f32_e32 v193, v193, v195
	v_add_f32_e32 v189, v189, v193
	v_add_f32_e32 v187, v187, v189
	s_waitcnt lgkmcnt(4)
	v_mfma_f32_32x32x16_bf16 v[32:47], v[220:223], v[80:83], v[32:47]
	v_mfma_f32_32x32x16_bf16 v[16:31], v[224:227], v[80:83], v[16:31]
	v_mfma_f32_32x32x16_bf16 v[32:47], v[228:231], v[84:87], v[32:47]
	v_mfma_f32_32x32x16_bf16 v[16:31], v[232:235], v[84:87], v[16:31]
	s_add_i32 s70, s70, 1
	s_cmp_le_u32 s70, s71
	s_cbranch_scc1 .Lat_m1_tile
	s_branch .Lpad_end
	s_nop 0
	s_nop 0
	s_nop 0
	s_nop 0
	s_nop 0
	s_nop 0
	s_nop 0
	s_nop 0
	s_nop 0
	s_nop 0
	s_nop 0
	s_nop 0
	s_nop 0
	s_nop 0
	s_nop 0
	s_nop 0
	s_nop 0
	s_nop 0
	s_nop 0
	s_nop 0
	s_nop 0
	s_nop 0
	s_nop 0
	s_nop 0
	s_nop 0
	s_nop 0
	s_nop 0
	s_nop 0
	s_nop 0
	s_nop 0
	s_nop 0
	s_nop 0
	s_nop 0
	s_nop 0
	s_nop 0
	s_nop 0
	s_nop 0
	s_nop 0
	s_nop 0
	s_nop 0
	s_nop 0
	s_nop 0
	s_nop 0
	s_nop 0
	s_nop 0
	s_nop 0
	s_nop 0
	s_nop 0
	s_nop 0
	s_nop 0
	s_nop 0
	s_nop 0
	s_nop 0
	s_nop 0
	s_nop 0
	s_nop 0
	s_nop 0
	s_nop 0
	s_nop 0
	s_nop 0
	s_nop 0
	s_nop 0
	s_nop 0
	s_nop 0
	s_nop 0
	s_nop 0
	s_nop 0
	s_nop 0
	s_nop 0
	s_nop 0
	s_nop 0
	s_nop 0
	s_nop 0
	s_nop 0
	s_nop 0
	s_nop 0
	s_nop 0
	s_nop 0
	s_nop 0
	s_nop 0
	s_nop 0
	s_nop 0
	s_nop 0
	s_nop 0
	s_nop 0
	s_nop 0
	s_nop 0
	s_nop 0
	s_nop 0
	s_nop 0
	s_nop 0
	s_nop 0
	s_nop 0
	s_nop 0
	s_nop 0
	s_nop 0
	s_nop 0
	s_nop 0
	s_nop 0
	s_nop 0
	s_nop 0
	s_nop 0
	s_nop 0
	s_nop 0
	s_nop 0
	s_nop 0
	s_nop 0
	s_nop 0
	s_nop 0
	s_nop 0
	s_nop 0
	s_nop 0
	s_nop 0
	s_nop 0
	s_nop 0
	s_nop 0
	s_nop 0
	s_nop 0
	s_nop 0
	s_nop 0
	s_nop 0
	s_nop 0
	s_nop 0
	s_nop 0
	s_nop 0
	s_nop 0
	s_nop 0
	s_nop 0
	s_nop 0
	s_nop 0
	s_nop 0
	s_nop 0
	s_nop 0
	s_nop 0
	s_nop 0
	s_nop 0
	s_nop 0
	s_nop 0
	s_nop 0
	s_nop 0
	s_nop 0
	s_nop 0
	s_nop 0
	s_nop 0
	s_nop 0
	s_nop 0
	s_nop 0
	s_nop 0
	s_nop 0
	s_nop 0
	s_nop 0
	s_nop 0
	s_nop 0
	s_nop 0
	s_nop 0
	s_nop 0
	s_nop 0
	s_nop 0
	s_nop 0
	s_nop 0
	s_nop 0
	s_nop 0
	s_nop 0
	s_nop 0
	s_nop 0
	s_nop 0
	s_nop 0
	s_nop 0
	s_nop 0
	s_nop 0
	s_nop 0
	s_nop 0
	s_nop 0
	s_nop 0
	s_nop 0
	s_nop 0
	s_nop 0
	s_nop 0
	s_nop 0
	s_nop 0
	s_nop 0
	s_nop 0
	s_nop 0
	s_nop 0
	s_nop 0
	s_nop 0
	s_nop 0
	s_nop 0
	s_nop 0
	s_nop 0
	s_nop 0
	s_nop 0
.Lpad_end:
	s_xor_b32 s33, s33, 1
	s_and_b64 vcc, exec, s[12:13]
	s_cbranch_vccz .LBB0_1200
	s_mul_i32 s0, s33, 0x8a00
	s_add_i32 s0, s0, 0
	v_add3_u32 v80, s0, v178, v144
	s_waitcnt vmcnt(2)
	ds_write_b128 v80, v[116:119]
	ds_write_b128 v80, v[112:115] offset:16
	v_lshl_add_u32 v80, v152, 1, s0
	s_waitcnt vmcnt(1)
	ds_write_b16 v80, v120 offset:18432
	ds_write_b16_d16_hi v80, v120 offset:18696
	ds_write_b16 v80, v121 offset:18960
	ds_write_b16_d16_hi v80, v121 offset:19224
	ds_write_b16 v80, v122 offset:19488
	ds_write_b16_d16_hi v80, v122 offset:19752
	ds_write_b16 v80, v123 offset:20016
	ds_write_b16_d16_hi v80, v123 offset:20280
	s_waitcnt vmcnt(0)
	ds_write_b16 v80, v124 offset:20544
	ds_write_b16_d16_hi v80, v124 offset:20808
	ds_write_b16 v80, v125 offset:21072
	ds_write_b16_d16_hi v80, v125 offset:21336
	ds_write_b16 v80, v126 offset:21600
	ds_write_b16_d16_hi v80, v126 offset:21864
	ds_write_b16 v80, v127 offset:22128
	ds_write_b16_d16_hi v80, v127 offset:22392
